# v23 + attention-B output epilogue: 16 staged-tile ds_read_b128 renamed to two alternating dead quads, read k+1 issued before the wait of read k (lgkmcnt(1))
# baseline (speedup 1.0000x reference)
; #define LAS __attribute__((address_space(3)))
; __device__ __forceinline__ int crow(int r, int hi) { return (r & 3) + 8 * (r >> 2) + 4 * hi; }
; __device__ __forceinline__ void row_recip(float l_reg, float (&rli)[16], LAS float* li, int r32, int hi) {
;     { auto rr = __builtin_amdgcn_permlane32_swap(__float_as_uint(l_reg), __float_as_uint(l_reg), false, false);
;       l_reg = __uint_as_float(rr[0]) + __uint_as_float(rr[1]); }
;     if (hi == 0) li[r32] = l_reg;
;     asm volatile("s_waitcnt lgkmcnt(0)" ::: "memory");
; #pragma unroll
;     for (int r = 0; r < 16; ++r) rli[r] = __builtin_amdgcn_rcpf(li[crow(r, hi)]);
;     asm volatile("s_waitcnt lgkmcnt(0)" ::: "memory");
; }
; template <bool SUBLN>
; __device__ __forceinline__ void attn_out(const AttnBufs& T, f32x16 (&o)[4], int type, int h, size_t orow0, LAS char* lds, int wid, int lane, int r32, int hi) {
;     const int rr = lane >> 5, c4 = (lane & 31) * 4;
;     const int col = type * 1024 + h * 128 + c4;
;     const bf16_t* gp = T.GATE + (orow0 + rr) * 3072 + col; bf16_t* op = T.BR + (orow0 + rr) * 3072 + col;
;     u32x2 gg[16];
; #pragma unroll
;     for (int i = 0; i < 16; ++i) gg[i] = *(const u32x2*)(gp + (size_t)i * 2 * 3072);
;     __syncthreads();
; __device__ __forceinline__ void attn_item(const AttnBufs& T, int type, int b, int h, int qrow0, int NT, LAS char* lds, int tid_) {
;     ...
;         for (int d0 = 0; d0 < 4; ++d0)
; #pragma unroll
;             for (int r = 0; r < 16; ++r) o[d0][r] *= rli[r];
.LBB0_147:
	s_waitcnt lgkmcnt(0)
	s_nop 11
	v_mov_b32_e32 v0, v202
	s_nop 1
	v_permlane32_swap_b32_e32 v202, v0
	v_cmp_gt_u32_e32 vcc, 32, v182
	s_and_saveexec_b64 s[56:57], vcc
	v_lshl_add_u32 v1, v181, 2, s90
	v_add_f32_e32 v0, v202, v0
	ds_write_b32 v1, v0
	s_or_b64 exec, exec, s[56:57]
	s_waitcnt lgkmcnt(0)
	v_add_u32_e32 v8, s90, v166
	ds_read_b128 v[0:3], v8
	ds_read_b128 v[4:7], v8 offset:32
	v_readlane_b32 s2, v251, 46
	v_readlane_b32 s3, v251, 47
	s_movk_i32 s4, 0x1800
	s_waitcnt lgkmcnt(0)
	v_rcp_f32_e32 v9, v0
	v_rcp_f32_e32 v10, v1
	v_rcp_f32_e32 v11, v2
	v_rcp_f32_e32 v12, v3
	ds_read_b128 v[0:3], v8 offset:64
	v_rcp_f32_e32 v4, v4
	v_rcp_f32_e32 v5, v5
	v_mul_f32_e32 v99, v34, v11
	v_mul_f32_e32 v100, v35, v12
	s_waitcnt lgkmcnt(0)
	v_rcp_f32_e32 v13, v0
	v_rcp_f32_e32 v14, v1
	v_rcp_f32_e32 v15, v2
	v_rcp_f32_e32 v80, v3
	ds_read_b128 v[0:3], v8 offset:96
	v_mov_b32_e32 v35, v177
	v_mul_f32_e32 v85, v20, v4
	v_mul_f32_e32 v86, v21, v5
	v_mul_f32_e32 v101, v36, v4
	s_waitcnt lgkmcnt(0)
	v_rcp_f32_e32 v0, v0
	v_rcp_f32_e32 v1, v1
	v_rcp_f32_e32 v2, v2
	v_rcp_f32_e32 v3, v3
	v_mul_f32_e32 v93, v28, v0
	v_mul_f32_e32 v44, v44, v0
	v_mul_f32_e32 v60, v60, v0
	v_mul_f32_e32 v76, v76, v0
	v_lshlrev_b32_e32 v0, 2, v182
	v_mul_f32_e32 v94, v29, v1
	v_mul_f32_e32 v95, v30, v2
	v_mul_f32_e32 v96, v31, v3
	v_mul_f32_e32 v45, v45, v1
	v_mul_f32_e32 v46, v46, v2
	v_mul_f32_e32 v47, v47, v3
	v_mul_f32_e32 v61, v61, v1
	v_mul_f32_e32 v62, v62, v2
	v_mul_f32_e32 v63, v63, v3
	v_mul_f32_e32 v77, v77, v1
	v_mul_f32_e32 v78, v78, v2
	v_mul_f32_e32 v79, v79, v3
	v_and_b32_e32 v34, 0x7c, v0
	v_lshl_add_u64 v[0:1], s[36:37], 0, v[176:177]
	v_mov_b64_e32 v[2:3], s[2:3]
	v_mul_f32_e32 v102, v37, v5
	v_mul_f32_e32 v52, v52, v4
	v_mul_f32_e32 v53, v53, v5
	v_mul_f32_e32 v68, v68, v4
	v_mul_f32_e32 v69, v69, v5
	v_mad_u64_u32 v[2:3], s[2:3], v0, s4, v[2:3]
	v_lshl_add_u64 v[4:5], v[34:35], 0, s[50:51]
	v_mul_f32_e32 v82, v17, v10
	v_mul_f32_e32 v83, v18, v11
	v_mul_f32_e32 v98, v33, v10
	v_mul_f32_e32 v49, v49, v10
	v_mul_f32_e32 v50, v50, v11
	v_mul_f32_e32 v65, v65, v10
	v_mul_f32_e32 v66, v66, v11
	v_mad_i32_i24 v3, v1, s4, v3
	v_lshlrev_b64 v[10:11], 1, v[4:5]
	s_waitcnt lgkmcnt(0)
	v_lshl_add_u64 v[2:3], v[2:3], 0, v[10:11]
	v_mul_f32_e32 v103, v40, v13
	v_mul_f32_e32 v104, v41, v14
	global_load_dwordx2 v[40:41], v[2:3], off offset:2048
	v_readlane_b32 s2, v251, 48
	v_readlane_b32 s3, v251, 49
	v_mul_f32_e32 v97, v32, v9
	v_mul_f32_e32 v91, v26, v15
	v_mov_b64_e32 v[4:5], s[2:3]
	v_mad_u64_u32 v[36:37], s[2:3], v0, s4, v[4:5]
	v_add_co_u32_e32 v0, vcc, s40, v2
	v_mad_i32_i24 v37, v1, s4, v37
	s_nop 0
	v_addc_co_u32_e32 v1, vcc, 0, v3, vcc
	global_load_dwordx2 v[32:33], v[0:1], off offset:2048
	v_add_co_u32_e32 v0, vcc, s82, v2
	s_mov_b32 s4, 0x9000
	s_nop 0
	v_addc_co_u32_e32 v1, vcc, 0, v3, vcc
	global_load_dwordx2 v[30:31], v[0:1], off offset:2048
	v_add_co_u32_e32 v0, vcc, s4, v2
	v_mul_f32_e32 v92, v27, v80
	s_nop 0
	v_addc_co_u32_e32 v1, vcc, 0, v3, vcc
	global_load_dwordx2 v[28:29], v[0:1], off offset:2048
	v_add_co_u32_e32 v0, vcc, s77, v2
	s_mov_b32 s5, 0xf000
	s_nop 0
	v_addc_co_u32_e32 v1, vcc, 0, v3, vcc
	global_load_dwordx2 v[26:27], v[0:1], off offset:2048
	v_rcp_f32_e32 v6, v6
	v_rcp_f32_e32 v7, v7
	v_add_co_u32_e32 v0, vcc, s5, v2
	v_mul_f32_e32 v89, v24, v13
	s_nop 0
	v_addc_co_u32_e32 v1, vcc, 0, v3, vcc
	v_mul_f32_e32 v90, v25, v14
	global_load_dwordx2 v[24:25], v[0:1], off offset:2048
	v_add_co_u32_e32 v0, vcc, s85, v2
	s_mov_b32 s20, 0x15000
	s_nop 0
	v_addc_co_u32_e32 v1, vcc, 0, v3, vcc
	v_mul_f32_e32 v87, v22, v6
	v_mul_f32_e32 v88, v23, v7
	global_load_dwordx2 v[22:23], v[0:1], off offset:2048
	v_add_co_u32_e32 v0, vcc, s20, v2
	s_mov_b32 s21, 0x1b000
	s_nop 0
	v_addc_co_u32_e32 v1, vcc, 0, v3, vcc
	global_load_dwordx2 v[20:21], v[0:1], off offset:2048
	v_add_co_u32_e32 v0, vcc, s76, v2
	v_mul_f32_e32 v84, v19, v12
	s_nop 0
	v_addc_co_u32_e32 v1, vcc, 0, v3, vcc
	global_load_dwordx2 v[18:19], v[0:1], off offset:2048
	v_add_co_u32_e32 v0, vcc, s21, v2
	v_mul_f32_e32 v81, v16, v9
	s_nop 0
	v_addc_co_u32_e32 v1, vcc, 0, v3, vcc
	global_load_dwordx2 v[16:17], v[0:1], off offset:2048
	v_add_co_u32_e32 v0, vcc, s92, v2
	s_mov_b32 s3, 0x21000
	s_nop 0
	v_addc_co_u32_e32 v1, vcc, 0, v3, vcc
	v_mul_f32_e32 v42, v42, v15
	v_mul_f32_e32 v57, v57, v14
	v_mul_f32_e32 v58, v58, v15
	v_mul_f32_e32 v73, v73, v14
	v_mul_f32_e32 v74, v74, v15
	global_load_dwordx2 v[14:15], v[0:1], off offset:2048
	v_add_co_u32_e32 v0, vcc, s3, v2
	v_mul_f32_e32 v51, v51, v12
	s_nop 0
	v_addc_co_u32_e32 v1, vcc, 0, v3, vcc
	v_mul_f32_e32 v56, v56, v13
	v_mul_f32_e32 v67, v67, v12
	v_mul_f32_e32 v72, v72, v13
	global_load_dwordx2 v[12:13], v[0:1], off offset:2048
	v_add_co_u32_e32 v0, vcc, s91, v2
	s_mov_b32 s33, 0x27000
	s_nop 0
	v_addc_co_u32_e32 v1, vcc, 0, v3, vcc
	v_mul_f32_e32 v48, v48, v9
	v_mul_f32_e32 v64, v64, v9
	global_load_dwordx2 v[8:9], v[0:1], off offset:2048
	v_add_co_u32_e32 v0, vcc, s33, v2
	v_mul_f32_e32 v38, v38, v6
	s_nop 0
	v_addc_co_u32_e32 v1, vcc, 0, v3, vcc
	v_mul_f32_e32 v39, v39, v7
	v_mul_f32_e32 v54, v54, v6
	v_mul_f32_e32 v55, v55, v7
	v_mul_f32_e32 v70, v70, v6
	v_mul_f32_e32 v71, v71, v7
	global_load_dwordx2 v[6:7], v[0:1], off offset:2048
	v_add_co_u32_e32 v0, vcc, s94, v2
	s_mov_b32 s2, 0x2d000
	s_nop 0
	v_addc_co_u32_e32 v1, vcc, 0, v3, vcc
	global_load_dwordx2 v[4:5], v[0:1], off offset:2048
	v_add_co_u32_e32 v0, vcc, s2, v2
	s_add_i32 s2, s73, 0
	s_nop 0
	v_addc_co_u32_e32 v1, vcc, 0, v3, vcc
	global_load_dwordx2 v[2:3], v[0:1], off offset:2048
	v_lshlrev_b32_e32 v0, 2, v181
	v_mul_u32_u24_e32 v1, 0x840, v176
	v_add3_u32 v0, s2, v0, v1
	v_mul_f32_e32 v43, v43, v80
	v_mul_f32_e32 v59, v59, v80
	v_mul_f32_e32 v75, v75, v80
	v_add_u32_e32 v1, 0x400, v0
	v_add_u32_e32 v35, 0x1000, v0
	v_add_u32_e32 v80, 0x1400, v0
	s_waitcnt vmcnt(0)
	s_barrier
; #define LAS __attribute__((address_space(3)))
; __device__ __forceinline__ float bf2f(unsigned h) { return __uint_as_float(h << 16); }
; __device__ __forceinline__ unsigned cvt_pk_bf16(float lo, float hi) { unsigned r; asm volatile("v_cvt_pk_bf16_f32 %0, %1, %2" : "=v"(r) : "v"(lo), "v"(hi)); return r; }
; __device__ __forceinline__ int crow(int r, int hi) { return (r & 3) + 8 * (r >> 2) + 4 * hi; }
; template <bool SUBLN>
; __device__ __forceinline__ void attn_out(const AttnBufs& T, f32x16 (&o)[4], int type, int h, size_t orow0, LAS char* lds, int wid, int lane, int r32, int hi) {
;     ...
;     LAS float* stg = (LAS float*)(lds + wid * 16896);
; #pragma unroll
;     for (int d0 = 0; d0 < 4; ++d0)
; #pragma unroll
;         for (int r = 0; r < 16; ++r) stg[att::crow(r, hi) * 132 + d0 * 32 + r32] = o[d0][r];
;     asm volatile("s_waitcnt lgkmcnt(0)" ::: "memory");
;     f32x4 wsub = {1.f, 1.f, 1.f, 1.f};
;     if (SUBLN) { wsub = *(const f32x4*)(T.subln + c4) * (1.f - T.lam_init); }
; #pragma unroll
;     for (int i = 0; i < 16; ++i) {
;         f32x4 v = *(const LAS f32x4*)(stg + (2 * i + rr) * 132 + c4);
;         if (SUBLN) {
;             float s = (v[0] * v[0] + v[1] * v[1]) + (v[2] * v[2] + v[3] * v[3]);
;             s += __shfl_xor(s, 1); s += __shfl_xor(s, 2); s += __shfl_xor(s, 4); s += __shfl_xor(s, 8); s += __shfl_xor(s, 16);
;             v = v * (rsqrtf(s * (1.f / 128.f) + EPS)) * wsub;
;         }
;         u32x2 w; w.x = cvt_pk_bf16(v[0] * bf2f(gg[i].x & 0xffffu), v[1] * bf2f(gg[i].x >> 16)); w.y = cvt_pk_bf16(v[2] * bf2f(gg[i].y & 0xffffu), v[3] * bf2f(gg[i].y >> 16));
;         *(u32x2*)(op + (size_t)i * 2 * 3072) = w;
;     }
	ds_write2_b32 v0, v81, v97 offset1:32
	ds_write2_b32 v0, v82, v98 offset0:132 offset1:164
	ds_write2_b32 v1, v83, v99 offset0:8 offset1:40
	ds_write2_b32 v1, v84, v100 offset0:140 offset1:172
	ds_write2_b32 v35, v85, v101 offset0:32 offset1:64
	ds_write2_b32 v35, v86, v102 offset0:164 offset1:196
	ds_write2_b32 v80, v87, v38 offset0:40 offset1:72
	ds_write2_b32 v80, v88, v39 offset0:172 offset1:204
	v_add_u32_e32 v38, 0x2000, v0
	v_add_u32_e32 v39, 0x2400, v0
	ds_write2_b32 v38, v89, v103 offset0:64 offset1:96
	ds_write2_b32 v38, v90, v104 offset0:196 offset1:228
	ds_write2_b32 v39, v91, v42 offset0:72 offset1:104
	ds_write2_b32 v39, v92, v43 offset0:204 offset1:236
	v_add_u32_e32 v42, 0x3000, v0
	v_add_u32_e32 v43, 0x3200, v0
	ds_write2_b32 v42, v93, v44 offset0:96 offset1:128
	ds_write2_b32 v43, v94, v45 offset0:100 offset1:132
	v_add_u32_e32 v43, 0x3400, v0
	v_add_u32_e32 v44, 0x3600, v0
	ds_write2_b32 v43, v95, v46 offset0:104 offset1:136
	ds_write2_b32 v44, v96, v47 offset0:108 offset1:140
	ds_write2_b32 v0, v48, v64 offset0:64 offset1:96
	ds_write2_b32 v0, v49, v65 offset0:196 offset1:228
	ds_write2_b32 v1, v50, v66 offset0:72 offset1:104
	ds_write2_b32 v1, v51, v67 offset0:204 offset1:236
	ds_write2_b32 v35, v52, v68 offset0:96 offset1:128
	v_add_u32_e32 v1, 0x1200, v0
	ds_write2_b32 v1, v53, v69 offset0:100 offset1:132
	ds_write2_b32 v80, v54, v70 offset0:104 offset1:136
	v_add_u32_e32 v1, 0x1600, v0
	ds_write2_b32 v1, v55, v71 offset0:108 offset1:140
	ds_write2_b32 v38, v56, v72 offset0:128 offset1:160
	ds_write2_b32 v39, v57, v73 offset0:4 offset1:36
	ds_write2_b32 v39, v58, v74 offset0:136 offset1:168
	v_add_u32_e32 v1, 0x2800, v0
	v_add_u32_e32 v0, 0x3800, v0
	ds_write2_b32 v1, v59, v75 offset0:12 offset1:44
	ds_write2_b32 v42, v60, v76 offset0:160 offset1:192
	ds_write2_b32 v43, v61, v77 offset0:36 offset1:68
	ds_write2_b32 v43, v62, v78 offset0:168 offset1:200
	ds_write2_b32 v0, v63, v79 offset0:44 offset1:76
	v_lshlrev_b32_e32 v34, 2, v34
	v_mul_u32_u24_e32 v35, 0x210, v176
	s_waitcnt lgkmcnt(0)
	v_add3_u32 v34, s2, v34, v35
	v_lshl_add_u64 v[10:11], v[36:37], 0, v[10:11]
	ds_read_b128 v[56:59], v34
	v_lshlrev_b32_e32 v35, 16, v40
	v_lshl_add_u64 v[0:1], v[10:11], 0, s[28:29]
	s_mov_b64 s[50:51], 0
	ds_read_b128 v[60:63], v34 offset:1056
	s_waitcnt lgkmcnt(1)
	v_mul_f32_e32 v35, v56, v35
	v_and_b32_e32 v36, 0xffff0000, v40
	v_mul_f32_e32 v36, v57, v36
	v_and_b32_e32 v37, 0xffff0000, v41
	v_cvt_pk_bf16_f32 v36, v35, v36
	v_lshlrev_b32_e32 v35, 16, v41
	v_mul_f32_e32 v37, v59, v37
	v_mul_f32_e32 v35, v58, v35
	v_cvt_pk_bf16_f32 v37, v35, v37
	global_store_dwordx2 v[10:11], v[36:37], off offset:2048
	v_lshlrev_b32_e32 v35, 16, v32
	v_and_b32_e32 v32, 0xffff0000, v32
	ds_read_b128 v[56:59], v34 offset:2112
	s_waitcnt lgkmcnt(1)
	v_mul_f32_e32 v35, v60, v35
	v_mul_f32_e32 v32, v61, v32
	v_cvt_pk_bf16_f32 v32, v35, v32
	v_lshlrev_b32_e32 v35, 16, v33
	v_and_b32_e32 v33, 0xffff0000, v33
	v_add_co_u32_e32 v36, vcc, s40, v10
	v_mul_f32_e32 v33, v63, v33
	s_nop 0
	v_addc_co_u32_e32 v37, vcc, 0, v11, vcc
	v_mul_f32_e32 v35, v62, v35
	v_cvt_pk_bf16_f32 v33, v35, v33
	global_store_dwordx2 v[36:37], v[32:33], off offset:2048
	v_lshlrev_b32_e32 v32, 16, v30
	v_and_b32_e32 v30, 0xffff0000, v30
	v_lshlrev_b32_e32 v35, 16, v28
	v_and_b32_e32 v28, 0xffff0000, v28
	ds_read_b128 v[60:63], v34 offset:3168
	s_waitcnt lgkmcnt(1)
	v_mul_f32_e32 v32, v56, v32
	v_mul_f32_e32 v30, v57, v30
	v_cvt_pk_bf16_f32 v30, v32, v30
	v_lshlrev_b32_e32 v32, 16, v31
	v_and_b32_e32 v31, 0xffff0000, v31
	v_mul_f32_e32 v32, v58, v32
	v_mul_f32_e32 v31, v59, v31
	v_cvt_pk_bf16_f32 v31, v32, v31
	v_add_co_u32_e32 v32, vcc, s82, v10
	s_nop 1
	v_addc_co_u32_e32 v33, vcc, 0, v11, vcc
	global_store_dwordx2 v[32:33], v[30:31], off offset:2048
	ds_read_b128 v[56:59], v34 offset:4224
	s_waitcnt lgkmcnt(1)
	v_mul_f32_e32 v30, v60, v35
	v_mul_f32_e32 v28, v61, v28
	v_cvt_pk_bf16_f32 v28, v30, v28
	v_lshlrev_b32_e32 v30, 16, v29
	v_and_b32_e32 v29, 0xffff0000, v29
	v_mul_f32_e32 v30, v62, v30
	v_mul_f32_e32 v29, v63, v29
	v_cvt_pk_bf16_f32 v29, v30, v29
	v_add_co_u32_e32 v30, vcc, s4, v10
	v_lshlrev_b32_e32 v32, 16, v26
	s_nop 0
	v_addc_co_u32_e32 v31, vcc, 0, v11, vcc
	global_store_dwordx2 v[30:31], v[28:29], off offset:2048
	v_and_b32_e32 v26, 0xffff0000, v26
	ds_read_b128 v[60:63], v34 offset:5280
	s_waitcnt lgkmcnt(1)
	v_mul_f32_e32 v28, v56, v32
	v_mul_f32_e32 v26, v57, v26
	v_cvt_pk_bf16_f32 v26, v28, v26
	v_lshlrev_b32_e32 v28, 16, v27
	v_and_b32_e32 v27, 0xffff0000, v27
	v_mul_f32_e32 v28, v58, v28
	v_mul_f32_e32 v27, v59, v27
	v_cvt_pk_bf16_f32 v27, v28, v27
	v_add_co_u32_e32 v28, vcc, s77, v10
	v_lshlrev_b32_e32 v30, 16, v24
	s_nop 0
	v_addc_co_u32_e32 v29, vcc, 0, v11, vcc
	global_store_dwordx2 v[28:29], v[26:27], off offset:2048
	v_and_b32_e32 v24, 0xffff0000, v24
	ds_read_b128 v[56:59], v34 offset:6336
	s_waitcnt lgkmcnt(1)
; #define LAS __attribute__((address_space(3)))
; __device__ __forceinline__ float bf2f(unsigned h) { return __uint_as_float(h << 16); }
; __device__ __forceinline__ unsigned cvt_pk_bf16(float lo, float hi) { unsigned r; asm volatile("v_cvt_pk_bf16_f32 %0, %1, %2" : "=v"(r) : "v"(lo), "v"(hi)); return r; }
; template <bool SUBLN>
; __device__ __forceinline__ void attn_out(const AttnBufs& T, f32x16 (&o)[4], int type, int h, size_t orow0, LAS char* lds, int wid, int lane, int r32, int hi) {
;     ...
;     for (int i = 0; i < 16; ++i) {
;         f32x4 v = *(const LAS f32x4*)(stg + (2 * i + rr) * 132 + c4);
;         if (SUBLN) {
;             float s = (v[0] * v[0] + v[1] * v[1]) + (v[2] * v[2] + v[3] * v[3]);
;             s += __shfl_xor(s, 1); s += __shfl_xor(s, 2); s += __shfl_xor(s, 4); s += __shfl_xor(s, 8); s += __shfl_xor(s, 16);
;             v = v * (rsqrtf(s * (1.f / 128.f) + EPS)) * wsub;
;         }
;         u32x2 w; w.x = cvt_pk_bf16(v[0] * bf2f(gg[i].x & 0xffffu), v[1] * bf2f(gg[i].x >> 16)); w.y = cvt_pk_bf16(v[2] * bf2f(gg[i].y & 0xffffu), v[3] * bf2f(gg[i].y >> 16));
;         *(u32x2*)(op + (size_t)i * 2 * 3072) = w;
;     }
	v_mul_f32_e32 v26, v60, v30
	v_mul_f32_e32 v24, v61, v24
	v_cvt_pk_bf16_f32 v24, v26, v24
	v_lshlrev_b32_e32 v26, 16, v25
	v_and_b32_e32 v25, 0xffff0000, v25
	v_mul_f32_e32 v26, v62, v26
	v_mul_f32_e32 v25, v63, v25
	v_cvt_pk_bf16_f32 v25, v26, v25
	v_add_co_u32_e32 v26, vcc, s5, v10
	v_lshlrev_b32_e32 v28, 16, v22
	s_nop 0
	v_addc_co_u32_e32 v27, vcc, 0, v11, vcc
	global_store_dwordx2 v[26:27], v[24:25], off offset:2048
	v_and_b32_e32 v22, 0xffff0000, v22
	ds_read_b128 v[60:63], v34 offset:7392
	s_waitcnt lgkmcnt(1)
	v_mul_f32_e32 v24, v56, v28
	v_mul_f32_e32 v22, v57, v22
	v_cvt_pk_bf16_f32 v22, v24, v22
	v_lshlrev_b32_e32 v24, 16, v23
	v_and_b32_e32 v23, 0xffff0000, v23
	v_mul_f32_e32 v24, v58, v24
	v_mul_f32_e32 v23, v59, v23
	v_cvt_pk_bf16_f32 v23, v24, v23
	v_add_co_u32_e32 v24, vcc, s85, v10
	v_lshlrev_b32_e32 v26, 16, v20
	s_nop 0
	v_addc_co_u32_e32 v25, vcc, 0, v11, vcc
	global_store_dwordx2 v[24:25], v[22:23], off offset:2048
	v_and_b32_e32 v20, 0xffff0000, v20
	ds_read_b128 v[56:59], v34 offset:8448
	s_waitcnt lgkmcnt(1)
	v_mul_f32_e32 v22, v60, v26
	v_mul_f32_e32 v20, v61, v20
	v_cvt_pk_bf16_f32 v20, v22, v20
	v_lshlrev_b32_e32 v22, 16, v21
	v_and_b32_e32 v21, 0xffff0000, v21
	v_mul_f32_e32 v22, v62, v22
	v_mul_f32_e32 v21, v63, v21
	v_cvt_pk_bf16_f32 v21, v22, v21
	v_add_co_u32_e32 v22, vcc, s20, v10
	v_lshlrev_b32_e32 v24, 16, v18
	s_nop 0
	v_addc_co_u32_e32 v23, vcc, 0, v11, vcc
	global_store_dwordx2 v[22:23], v[20:21], off offset:2048
	v_and_b32_e32 v18, 0xffff0000, v18
	ds_read_b128 v[60:63], v34 offset:9504
	s_waitcnt lgkmcnt(1)
	v_mul_f32_e32 v20, v56, v24
	v_mul_f32_e32 v18, v57, v18
	v_cvt_pk_bf16_f32 v18, v20, v18
	v_lshlrev_b32_e32 v20, 16, v19
	v_and_b32_e32 v19, 0xffff0000, v19
	v_mul_f32_e32 v20, v58, v20
	v_mul_f32_e32 v19, v59, v19
	v_cvt_pk_bf16_f32 v19, v20, v19
	v_add_co_u32_e32 v20, vcc, s76, v10
	v_lshlrev_b32_e32 v22, 16, v16
	s_nop 0
	v_addc_co_u32_e32 v21, vcc, 0, v11, vcc
	global_store_dwordx2 v[20:21], v[18:19], off offset:2048
	v_and_b32_e32 v16, 0xffff0000, v16
	ds_read_b128 v[56:59], v34 offset:10560
	s_waitcnt lgkmcnt(1)
	v_mul_f32_e32 v18, v60, v22
	v_mul_f32_e32 v16, v61, v16
	v_cvt_pk_bf16_f32 v16, v18, v16
	v_lshlrev_b32_e32 v18, 16, v17
	v_and_b32_e32 v17, 0xffff0000, v17
	v_mul_f32_e32 v18, v62, v18
	v_mul_f32_e32 v17, v63, v17
	v_cvt_pk_bf16_f32 v17, v18, v17
	v_add_co_u32_e32 v18, vcc, s21, v10
	v_lshlrev_b32_e32 v20, 16, v14
	s_nop 0
	v_addc_co_u32_e32 v19, vcc, 0, v11, vcc
	global_store_dwordx2 v[18:19], v[16:17], off offset:2048
	v_and_b32_e32 v14, 0xffff0000, v14
	ds_read_b128 v[60:63], v34 offset:11616
	s_waitcnt lgkmcnt(1)
	v_mul_f32_e32 v16, v56, v20
	v_mul_f32_e32 v14, v57, v14
	v_cvt_pk_bf16_f32 v14, v16, v14
	v_lshlrev_b32_e32 v16, 16, v15
	v_and_b32_e32 v15, 0xffff0000, v15
	v_mul_f32_e32 v16, v58, v16
	v_mul_f32_e32 v15, v59, v15
	v_cvt_pk_bf16_f32 v15, v16, v15
	v_add_co_u32_e32 v16, vcc, s92, v10
	v_lshlrev_b32_e32 v18, 16, v12
	s_nop 0
	v_addc_co_u32_e32 v17, vcc, 0, v11, vcc
	global_store_dwordx2 v[16:17], v[14:15], off offset:2048
	v_and_b32_e32 v12, 0xffff0000, v12
	ds_read_b128 v[56:59], v34 offset:12672
	s_waitcnt lgkmcnt(1)
	v_mul_f32_e32 v14, v60, v18
	v_mul_f32_e32 v12, v61, v12
	v_cvt_pk_bf16_f32 v12, v14, v12
	v_lshlrev_b32_e32 v14, 16, v13
	v_and_b32_e32 v13, 0xffff0000, v13
	v_mul_f32_e32 v14, v62, v14
	v_mul_f32_e32 v13, v63, v13
	v_cvt_pk_bf16_f32 v13, v14, v13
	v_add_co_u32_e32 v14, vcc, s3, v10
	v_lshlrev_b32_e32 v16, 16, v8
	s_nop 0
	v_addc_co_u32_e32 v15, vcc, 0, v11, vcc
	global_store_dwordx2 v[14:15], v[12:13], off offset:2048
	v_and_b32_e32 v8, 0xffff0000, v8
	ds_read_b128 v[60:63], v34 offset:13728
	s_waitcnt lgkmcnt(1)
	v_mul_f32_e32 v12, v56, v16
	v_mul_f32_e32 v8, v57, v8
	v_cvt_pk_bf16_f32 v8, v12, v8
	v_lshlrev_b32_e32 v12, 16, v9
	v_and_b32_e32 v9, 0xffff0000, v9
	v_mul_f32_e32 v12, v58, v12
	v_mul_f32_e32 v9, v59, v9
	v_cvt_pk_bf16_f32 v9, v12, v9
	v_add_co_u32_e32 v12, vcc, s91, v10
	s_nop 1
	v_addc_co_u32_e32 v13, vcc, 0, v11, vcc
	global_store_dwordx2 v[12:13], v[8:9], off offset:2048
	v_lshlrev_b32_e32 v8, 16, v6
	v_and_b32_e32 v6, 0xffff0000, v6
	ds_read_b128 v[56:59], v34 offset:14784
	s_waitcnt lgkmcnt(1)
	v_mul_f32_e32 v8, v60, v8
	v_mul_f32_e32 v6, v61, v6
	v_cvt_pk_bf16_f32 v6, v8, v6
	v_lshlrev_b32_e32 v8, 16, v7
	v_and_b32_e32 v7, 0xffff0000, v7
	v_mul_f32_e32 v8, v62, v8
	v_mul_f32_e32 v7, v63, v7
	v_cvt_pk_bf16_f32 v7, v8, v7
	v_add_co_u32_e32 v8, vcc, s33, v10
	v_lshlrev_b32_e32 v12, 16, v4
	s_nop 0
	v_addc_co_u32_e32 v9, vcc, 0, v11, vcc
	global_store_dwordx2 v[8:9], v[6:7], off offset:2048
	v_and_b32_e32 v4, 0xffff0000, v4
	ds_read_b128 v[60:63], v34 offset:15840
	s_waitcnt lgkmcnt(1)
	v_mul_f32_e32 v6, v56, v12
	v_mul_f32_e32 v4, v57, v4
	v_cvt_pk_bf16_f32 v4, v6, v4
	v_lshlrev_b32_e32 v6, 16, v5
	v_and_b32_e32 v5, 0xffff0000, v5
	v_mul_f32_e32 v6, v58, v6
	v_mul_f32_e32 v5, v59, v5
	v_cvt_pk_bf16_f32 v5, v6, v5
	v_add_co_u32_e32 v6, vcc, s94, v10
	v_lshlrev_b32_e32 v8, 16, v2
	s_nop 0
	v_addc_co_u32_e32 v7, vcc, 0, v11, vcc
	global_store_dwordx2 v[6:7], v[4:5], off offset:2048
	v_and_b32_e32 v2, 0xffff0000, v2
	s_waitcnt lgkmcnt(0)
	v_mul_f32_e32 v4, v60, v8
	v_mul_f32_e32 v2, v61, v2
	v_cvt_pk_bf16_f32 v2, v4, v2
	v_lshlrev_b32_e32 v4, 16, v3
	v_and_b32_e32 v3, 0xffff0000, v3
	v_mul_f32_e32 v3, v63, v3
	v_mul_f32_e32 v4, v62, v4
	v_cvt_pk_bf16_f32 v3, v4, v3
